# P6: the 8 row sum-of-squares values of each unit are loaded in the peeled first K-iteration into spare registers, the epilogue no longer loads them; on top of block-major H
# speedup vs baseline: 1.0237x; 1.0003x over previous
.LBB0_663:
	s_ashr_i32 s13, s12, 31
	s_lshl_b64 s[16:17], s[12:13], 19
	s_add_u32 s18, s60, s16
	s_addc_u32 s19, s61, s17
	s_and_b64 s[16:17], s[36:37], exec
	s_cselect_b32 s13, s19, s15
	s_cselect_b32 s78, s18, s14
	s_ashr_i32 s11, s10, 31
	s_lshl_b64 s[16:17], s[10:11], 19
	s_add_u32 s16, s3, s16
	s_addc_u32 s17, s26, s17
	s_and_b64 s[22:23], s[36:37], exec
	s_cselect_b32 s11, s17, s21
	s_cselect_b32 s79, s16, s20
	s_add_u32 s80, s20, 0x100
	s_addc_u32 s81, s21, 0
	s_mov_b32 s86, -2
	ds_read_b128 v[142:145], v155
	ds_read_b128 v[160:163], v155 offset:1024
	ds_read_b128 v[166:169], v155 offset:2048
	ds_read_b128 v[170:173], v155 offset:3072
	ds_read_b128 v[174:177], v156
	ds_read_b128 v[178:181], v156 offset:1024
	ds_read_b128 v[182:185], v156 offset:2048
	ds_read_b128 v[186:189], v156 offset:3072
	s_add_u32 vcc_lo, s14, 0x100
	s_addc_u32 vcc_hi, s15, 0
	s_cmp_eq_u32 s86, 12
	s_cselect_b32 s24, s78, vcc_lo
	s_cselect_b32 s25, s13, vcc_hi
	s_cselect_b32 s22, s79, s80
	s_cselect_b32 s23, s11, s81
	s_add_u32 s20, s24, 0x80
	s_addc_u32 s21, s25, 0
	ds_read_b128 v[190:193], v157
	ds_read_b128 v[194:197], v157 offset:1024
	ds_read_b128 v[198:201], v157 offset:2048
	ds_read_b128 v[202:205], v157 offset:3072
	ds_read_b128 v[206:209], v157 offset:4096
	ds_read_b128 v[210:213], v157 offset:5120
	ds_read_b128 v[214:217], v157 offset:6144
	ds_read_b128 v[218:221], v157 offset:7168
	s_add_u32 s14, s14, 0x40080
	s_addc_u32 s15, s15, 0
	s_mov_b32 s87, m0
	s_mov_b32 m0, s82
	s_nop 0
	global_load_lds_dwordx4 v150, s[14:15]
	s_mov_b32 m0, s87
	s_add_i32 s87, s30, 0xe000
	s_mov_b32 s90, m0
	s_mov_b32 m0, s87
	s_nop 0
	global_load_lds_dwordx4 v152, s[14:15]
	s_mov_b32 m0, s90
	s_waitcnt vmcnt(8)
	v_lshl_add_u32 v244, s77, 8, v154
	v_lshlrev_b32_e32 v244, 2, v244
	global_load_dword v248, v244, s[6:7]
	global_load_dword v249, v244, s[6:7] offset:64
	global_load_dword v250, v244, s[6:7] offset:128
	global_load_dword v251, v244, s[6:7] offset:192
	global_load_dword v252, v244, s[6:7] offset:512
	global_load_dword v253, v244, s[6:7] offset:576
	global_load_dword v254, v244, s[6:7] offset:640
	global_load_dword v255, v244, s[6:7] offset:704
	s_waitcnt lgkmcnt(0)
	s_barrier
	s_setprio 1
	s_waitcnt lgkmcnt(7)
	v_mfma_f32_16x16x32_bf16 v[124:127], v[142:145], v[190:193], 0
	v_mfma_f32_16x16x32_bf16 v[120:123], v[166:169], v[190:193], 0
	s_waitcnt lgkmcnt(5)
	v_mfma_f32_16x16x32_bf16 v[108:111], v[142:145], v[198:201], 0
	v_mfma_f32_16x16x32_bf16 v[104:107], v[166:169], v[198:201], 0
	s_waitcnt lgkmcnt(3)
	v_mfma_f32_16x16x32_bf16 v[92:95], v[142:145], v[206:209], 0
	v_mfma_f32_16x16x32_bf16 v[88:91], v[166:169], v[206:209], 0
	s_waitcnt lgkmcnt(1)
	v_mfma_f32_16x16x32_bf16 v[76:79], v[142:145], v[214:217], 0
	v_mfma_f32_16x16x32_bf16 v[72:75], v[166:169], v[214:217], 0
	v_mfma_f32_16x16x32_bf16 v[124:127], v[160:163], v[194:197], v[124:127]
	v_mfma_f32_16x16x32_bf16 v[120:123], v[170:173], v[194:197], v[120:123]
	v_mfma_f32_16x16x32_bf16 v[108:111], v[160:163], v[202:205], v[108:111]
	v_mfma_f32_16x16x32_bf16 v[104:107], v[170:173], v[202:205], v[104:107]
	v_mfma_f32_16x16x32_bf16 v[92:95], v[160:163], v[210:213], v[92:95]
	v_mfma_f32_16x16x32_bf16 v[88:91], v[170:173], v[210:213], v[88:91]
	s_waitcnt lgkmcnt(0)
	v_mfma_f32_16x16x32_bf16 v[76:79], v[160:163], v[218:221], v[76:79]
	v_mfma_f32_16x16x32_bf16 v[72:75], v[170:173], v[218:221], v[72:75]
	s_setprio 0
	s_setprio 1
	v_mfma_f32_16x16x32_bf16 v[116:119], v[174:177], v[190:193], 0
	v_mfma_f32_16x16x32_bf16 v[112:115], v[182:185], v[190:193], 0
	v_mfma_f32_16x16x32_bf16 v[100:103], v[174:177], v[198:201], 0
	v_mfma_f32_16x16x32_bf16 v[96:99], v[182:185], v[198:201], 0
	v_mfma_f32_16x16x32_bf16 v[84:87], v[174:177], v[206:209], 0
	v_mfma_f32_16x16x32_bf16 v[80:83], v[182:185], v[206:209], 0
	v_mfma_f32_16x16x32_bf16 v[68:71], v[174:177], v[214:217], 0
	v_mfma_f32_16x16x32_bf16 v[64:67], v[182:185], v[214:217], 0
	v_mfma_f32_16x16x32_bf16 v[116:119], v[178:181], v[194:197], v[116:119]
	v_mfma_f32_16x16x32_bf16 v[112:115], v[186:189], v[194:197], v[112:115]
	v_mfma_f32_16x16x32_bf16 v[100:103], v[178:181], v[202:205], v[100:103]
	v_mfma_f32_16x16x32_bf16 v[96:99], v[186:189], v[202:205], v[96:99]
	v_mfma_f32_16x16x32_bf16 v[84:87], v[178:181], v[210:213], v[84:87]
	v_mfma_f32_16x16x32_bf16 v[80:83], v[186:189], v[210:213], v[80:83]
	v_mfma_f32_16x16x32_bf16 v[68:71], v[178:181], v[218:221], v[68:71]
	v_mfma_f32_16x16x32_bf16 v[64:67], v[186:189], v[218:221], v[64:67]
	s_setprio 0
	s_barrier
	ds_read_b128 v[190:193], v157 offset:16384
	ds_read_b128 v[194:197], v157 offset:17408
	ds_read_b128 v[198:201], v157 offset:18432
	ds_read_b128 v[202:205], v157 offset:19456
	ds_read_b128 v[206:209], v157 offset:20480
	ds_read_b128 v[210:213], v157 offset:21504
	ds_read_b128 v[214:217], v157 offset:22528
	ds_read_b128 v[218:221], v157 offset:23552
	s_mov_b32 s14, m0
	s_mov_b32 m0, s31
	s_nop 0
	global_load_lds_dwordx4 v151, s[22:23]
	s_mov_b32 m0, s14
	s_nop 0
	s_mov_b32 s14, m0
	s_mov_b32 m0, s34
	s_nop 0
	global_load_lds_dwordx4 v153, s[22:23]
	s_mov_b32 m0, s14
	s_add_u32 s14, s22, 0x40000
	s_addc_u32 s15, s23, 0
	s_mov_b32 s87, m0
	s_mov_b32 m0, s35
	s_nop 0
	global_load_lds_dwordx4 v151, s[14:15]
	s_mov_b32 m0, s87
	s_nop 0
	s_mov_b32 s87, m0
	s_mov_b32 m0, s38
	s_nop 0
	global_load_lds_dwordx4 v153, s[14:15]
	s_mov_b32 m0, s87
	s_mov_b32 s14, m0
	s_mov_b32 m0, s30
	s_nop 0
	global_load_lds_dwordx4 v150, s[24:25]
	s_mov_b32 m0, s14
	s_nop 0
	s_mov_b32 s14, m0
	s_mov_b32 m0, s39
	s_nop 0
	global_load_lds_dwordx4 v152, s[24:25]
	s_mov_b32 m0, s14
	s_waitcnt vmcnt(16)
	s_waitcnt lgkmcnt(0)
	s_barrier
	s_setprio 1
	s_waitcnt lgkmcnt(7)
	v_mfma_f32_16x16x32_bf16 v[60:63], v[142:145], v[190:193], 0
	v_mfma_f32_16x16x32_bf16 v[56:59], v[166:169], v[190:193], 0
	s_waitcnt lgkmcnt(5)
	v_mfma_f32_16x16x32_bf16 v[44:47], v[142:145], v[198:201], 0
	v_mfma_f32_16x16x32_bf16 v[40:43], v[166:169], v[198:201], 0
	s_waitcnt lgkmcnt(3)
	v_mfma_f32_16x16x32_bf16 v[28:31], v[142:145], v[206:209], 0
	v_mfma_f32_16x16x32_bf16 v[24:27], v[166:169], v[206:209], 0
	s_waitcnt lgkmcnt(1)
	v_mfma_f32_16x16x32_bf16 v[12:15], v[142:145], v[214:217], 0
	v_mfma_f32_16x16x32_bf16 v[8:11], v[166:169], v[214:217], 0
	v_mfma_f32_16x16x32_bf16 v[60:63], v[160:163], v[194:197], v[60:63]
	v_mfma_f32_16x16x32_bf16 v[56:59], v[170:173], v[194:197], v[56:59]
	v_mfma_f32_16x16x32_bf16 v[44:47], v[160:163], v[202:205], v[44:47]
	v_mfma_f32_16x16x32_bf16 v[40:43], v[170:173], v[202:205], v[40:43]
	v_mfma_f32_16x16x32_bf16 v[28:31], v[160:163], v[210:213], v[28:31]
	v_mfma_f32_16x16x32_bf16 v[24:27], v[170:173], v[210:213], v[24:27]
	s_waitcnt lgkmcnt(0)
	v_mfma_f32_16x16x32_bf16 v[12:15], v[160:163], v[218:221], v[12:15]
	v_mfma_f32_16x16x32_bf16 v[8:11], v[170:173], v[218:221], v[8:11]
	s_setprio 0
	s_setprio 1
	v_mfma_f32_16x16x32_bf16 v[52:55], v[174:177], v[190:193], 0
	v_mfma_f32_16x16x32_bf16 v[48:51], v[182:185], v[190:193], 0
	v_mfma_f32_16x16x32_bf16 v[36:39], v[174:177], v[198:201], 0
	v_mfma_f32_16x16x32_bf16 v[32:35], v[182:185], v[198:201], 0
	v_mfma_f32_16x16x32_bf16 v[20:23], v[174:177], v[206:209], 0
	v_mfma_f32_16x16x32_bf16 v[16:19], v[182:185], v[206:209], 0
	v_mfma_f32_16x16x32_bf16 v[4:7], v[174:177], v[214:217], 0
	v_mfma_f32_16x16x32_bf16 v[0:3], v[182:185], v[214:217], 0
	v_mfma_f32_16x16x32_bf16 v[52:55], v[178:181], v[194:197], v[52:55]
	v_mfma_f32_16x16x32_bf16 v[48:51], v[186:189], v[194:197], v[48:51]
	v_mfma_f32_16x16x32_bf16 v[36:39], v[178:181], v[202:205], v[36:39]
	v_mfma_f32_16x16x32_bf16 v[32:35], v[186:189], v[202:205], v[32:35]
	v_mfma_f32_16x16x32_bf16 v[20:23], v[178:181], v[210:213], v[20:23]
	v_mfma_f32_16x16x32_bf16 v[16:19], v[186:189], v[210:213], v[16:19]
	v_mfma_f32_16x16x32_bf16 v[4:7], v[178:181], v[218:221], v[4:7]
	v_mfma_f32_16x16x32_bf16 v[0:3], v[186:189], v[218:221], v[0:3]
	s_setprio 0
	s_barrier
	ds_read_b128 v[142:145], v158
	ds_read_b128 v[160:163], v158 offset:1024
	ds_read_b128 v[166:169], v158 offset:2048
	ds_read_b128 v[170:173], v158 offset:3072
	ds_read_b128 v[174:177], v159
	ds_read_b128 v[178:181], v159 offset:1024
	ds_read_b128 v[182:185], v159 offset:2048
	ds_read_b128 v[186:189], v159 offset:3072
	ds_read_b128 v[190:193], v157 offset:32768
	ds_read_b128 v[194:197], v157 offset:33792
	ds_read_b128 v[198:201], v157 offset:34816
	ds_read_b128 v[202:205], v157 offset:35840
	ds_read_b128 v[206:209], v157 offset:36864
	ds_read_b128 v[210:213], v157 offset:37888
	ds_read_b128 v[214:217], v157 offset:38912
	ds_read_b128 v[218:221], v157 offset:39936
	s_add_u32 s14, s24, 0x40000
	s_addc_u32 s15, s25, 0
	s_mov_b32 s24, m0
	s_mov_b32 m0, s40
	s_nop 0
	global_load_lds_dwordx4 v150, s[14:15]
	s_mov_b32 m0, s24
	s_nop 0
	s_mov_b32 s24, m0
	s_mov_b32 m0, s41
	s_nop 0
	global_load_lds_dwordx4 v152, s[14:15]
	s_mov_b32 m0, s24
	s_waitcnt vmcnt(16)
	s_waitcnt lgkmcnt(0)
	s_barrier
	s_setprio 1
	s_waitcnt lgkmcnt(7)
	v_mfma_f32_16x16x32_bf16 v[124:127], v[142:145], v[190:193], v[124:127]
	v_mfma_f32_16x16x32_bf16 v[120:123], v[166:169], v[190:193], v[120:123]
	s_waitcnt lgkmcnt(5)
	v_mfma_f32_16x16x32_bf16 v[108:111], v[142:145], v[198:201], v[108:111]
	v_mfma_f32_16x16x32_bf16 v[104:107], v[166:169], v[198:201], v[104:107]
	s_waitcnt lgkmcnt(3)
	v_mfma_f32_16x16x32_bf16 v[92:95], v[142:145], v[206:209], v[92:95]
	v_mfma_f32_16x16x32_bf16 v[88:91], v[166:169], v[206:209], v[88:91]
	s_waitcnt lgkmcnt(1)
	v_mfma_f32_16x16x32_bf16 v[76:79], v[142:145], v[214:217], v[76:79]
	v_mfma_f32_16x16x32_bf16 v[72:75], v[166:169], v[214:217], v[72:75]
	v_mfma_f32_16x16x32_bf16 v[124:127], v[160:163], v[194:197], v[124:127]
	v_mfma_f32_16x16x32_bf16 v[120:123], v[170:173], v[194:197], v[120:123]
	v_mfma_f32_16x16x32_bf16 v[108:111], v[160:163], v[202:205], v[108:111]
	v_mfma_f32_16x16x32_bf16 v[104:107], v[170:173], v[202:205], v[104:107]
	v_mfma_f32_16x16x32_bf16 v[92:95], v[160:163], v[210:213], v[92:95]
	v_mfma_f32_16x16x32_bf16 v[88:91], v[170:173], v[210:213], v[88:91]
	s_waitcnt lgkmcnt(0)
	v_mfma_f32_16x16x32_bf16 v[76:79], v[160:163], v[218:221], v[76:79]
	v_mfma_f32_16x16x32_bf16 v[72:75], v[170:173], v[218:221], v[72:75]
	s_setprio 0
	s_setprio 1
	v_mfma_f32_16x16x32_bf16 v[116:119], v[174:177], v[190:193], v[116:119]
	v_mfma_f32_16x16x32_bf16 v[112:115], v[182:185], v[190:193], v[112:115]
	v_mfma_f32_16x16x32_bf16 v[100:103], v[174:177], v[198:201], v[100:103]
	v_mfma_f32_16x16x32_bf16 v[96:99], v[182:185], v[198:201], v[96:99]
	v_mfma_f32_16x16x32_bf16 v[84:87], v[174:177], v[206:209], v[84:87]
	v_mfma_f32_16x16x32_bf16 v[80:83], v[182:185], v[206:209], v[80:83]
	v_mfma_f32_16x16x32_bf16 v[68:71], v[174:177], v[214:217], v[68:71]
	v_mfma_f32_16x16x32_bf16 v[64:67], v[182:185], v[214:217], v[64:67]
	v_mfma_f32_16x16x32_bf16 v[116:119], v[178:181], v[194:197], v[116:119]
	v_mfma_f32_16x16x32_bf16 v[112:115], v[186:189], v[194:197], v[112:115]
	v_mfma_f32_16x16x32_bf16 v[100:103], v[178:181], v[202:205], v[100:103]
	v_mfma_f32_16x16x32_bf16 v[96:99], v[186:189], v[202:205], v[96:99]
	v_mfma_f32_16x16x32_bf16 v[84:87], v[178:181], v[210:213], v[84:87]
	v_mfma_f32_16x16x32_bf16 v[80:83], v[186:189], v[210:213], v[80:83]
	v_mfma_f32_16x16x32_bf16 v[68:71], v[178:181], v[218:221], v[68:71]
	v_mfma_f32_16x16x32_bf16 v[64:67], v[186:189], v[218:221], v[64:67]
	s_setprio 0
	s_barrier
	ds_read_b128 v[190:193], v157 offset:49152
	ds_read_b128 v[194:197], v157 offset:50176
	ds_read_b128 v[198:201], v157 offset:51200
	ds_read_b128 v[202:205], v157 offset:52224
	ds_read_b128 v[206:209], v157 offset:53248
	ds_read_b128 v[210:213], v157 offset:54272
	ds_read_b128 v[214:217], v157 offset:55296
	ds_read_b128 v[218:221], v157 offset:56320
	s_add_u32 s14, s22, 0x80
	s_addc_u32 s15, s23, 0
	s_mov_b32 s24, m0
	s_mov_b32 m0, s44
	s_nop 0
	global_load_lds_dwordx4 v151, s[14:15]
	s_mov_b32 m0, s24
	s_nop 0
	s_mov_b32 s24, m0
	s_mov_b32 m0, s45
	s_nop 0
	global_load_lds_dwordx4 v153, s[14:15]
	s_mov_b32 m0, s24
	s_add_u32 s14, s22, 0x40080
	s_addc_u32 s15, s23, 0
	s_mov_b32 s22, m0
	s_mov_b32 m0, s66
	s_nop 0
	global_load_lds_dwordx4 v151, s[14:15]
	s_mov_b32 m0, s22
	s_nop 0
	s_mov_b32 s22, m0
	s_mov_b32 m0, s67
	s_nop 0
	global_load_lds_dwordx4 v153, s[14:15]
	s_mov_b32 m0, s22
	s_mov_b32 s14, m0
	s_mov_b32 m0, s64
	s_nop 0
	global_load_lds_dwordx4 v150, s[20:21]
	s_mov_b32 m0, s14
	s_nop 0
	s_mov_b32 s14, m0
	s_mov_b32 m0, s65
	s_nop 0
	global_load_lds_dwordx4 v152, s[20:21]
	s_mov_b32 m0, s14
	s_waitcnt vmcnt(8)
	s_waitcnt lgkmcnt(0)
	s_barrier
	s_setprio 1
	s_waitcnt lgkmcnt(7)
	v_mfma_f32_16x16x32_bf16 v[60:63], v[142:145], v[190:193], v[60:63]
	v_mfma_f32_16x16x32_bf16 v[56:59], v[166:169], v[190:193], v[56:59]
	s_waitcnt lgkmcnt(5)
	v_mfma_f32_16x16x32_bf16 v[44:47], v[142:145], v[198:201], v[44:47]
	v_mfma_f32_16x16x32_bf16 v[40:43], v[166:169], v[198:201], v[40:43]
	s_waitcnt lgkmcnt(3)
	v_mfma_f32_16x16x32_bf16 v[28:31], v[142:145], v[206:209], v[28:31]
	v_mfma_f32_16x16x32_bf16 v[24:27], v[166:169], v[206:209], v[24:27]
	s_waitcnt lgkmcnt(1)
	v_mfma_f32_16x16x32_bf16 v[12:15], v[142:145], v[214:217], v[12:15]
	v_mfma_f32_16x16x32_bf16 v[8:11], v[166:169], v[214:217], v[8:11]
	v_mfma_f32_16x16x32_bf16 v[60:63], v[160:163], v[194:197], v[60:63]
	v_mfma_f32_16x16x32_bf16 v[56:59], v[170:173], v[194:197], v[56:59]
	v_mfma_f32_16x16x32_bf16 v[44:47], v[160:163], v[202:205], v[44:47]
	v_mfma_f32_16x16x32_bf16 v[40:43], v[170:173], v[202:205], v[40:43]
	v_mfma_f32_16x16x32_bf16 v[28:31], v[160:163], v[210:213], v[28:31]
	v_mfma_f32_16x16x32_bf16 v[24:27], v[170:173], v[210:213], v[24:27]
	s_waitcnt lgkmcnt(0)
	v_mfma_f32_16x16x32_bf16 v[12:15], v[160:163], v[218:221], v[12:15]
	v_mfma_f32_16x16x32_bf16 v[8:11], v[170:173], v[218:221], v[8:11]
	s_setprio 0
	s_setprio 1
	v_mfma_f32_16x16x32_bf16 v[52:55], v[174:177], v[190:193], v[52:55]
	v_mfma_f32_16x16x32_bf16 v[48:51], v[182:185], v[190:193], v[48:51]
	v_mfma_f32_16x16x32_bf16 v[36:39], v[174:177], v[198:201], v[36:39]
	v_mfma_f32_16x16x32_bf16 v[32:35], v[182:185], v[198:201], v[32:35]
	v_mfma_f32_16x16x32_bf16 v[20:23], v[174:177], v[206:209], v[20:23]
	v_mfma_f32_16x16x32_bf16 v[16:19], v[182:185], v[206:209], v[16:19]
	v_mfma_f32_16x16x32_bf16 v[4:7], v[174:177], v[214:217], v[4:7]
	v_mfma_f32_16x16x32_bf16 v[0:3], v[182:185], v[214:217], v[0:3]
	v_mfma_f32_16x16x32_bf16 v[52:55], v[178:181], v[194:197], v[52:55]
	v_mfma_f32_16x16x32_bf16 v[48:51], v[186:189], v[194:197], v[48:51]
	v_mfma_f32_16x16x32_bf16 v[36:39], v[178:181], v[202:205], v[36:39]
	v_mfma_f32_16x16x32_bf16 v[32:35], v[186:189], v[202:205], v[32:35]
	v_mfma_f32_16x16x32_bf16 v[20:23], v[178:181], v[210:213], v[20:23]
	v_mfma_f32_16x16x32_bf16 v[16:19], v[186:189], v[210:213], v[16:19]
	v_mfma_f32_16x16x32_bf16 v[4:7], v[178:181], v[218:221], v[4:7]
	v_mfma_f32_16x16x32_bf16 v[0:3], v[186:189], v[218:221], v[0:3]
	s_setprio 0
	s_barrier
	s_add_i32 s86, s86, 2
	s_add_u32 s80, s80, 0x100
	s_addc_u32 s81, s81, 0
	s_cmp_gt_u32 s86, 13
	s_mov_b64 s[14:15], vcc
	s_branch .LBB0_664

.LBB0_667:
	v_lshl_add_u32 v222, s77, 8, v154
	v_lshlrev_b32_e32 v223, 2, v222
	s_lshl_b32 s14, s77, 21
	s_lshl_b32 s15, s76, 13
	s_add_i32 s14, s14, s15
	v_and_b32_e32 v224, 15, v165
	v_lshlrev_b32_e32 v224, 6, v224
	v_and_b32_e32 v225, 0x30, v165
	v_or_b32_e32 v224, v224, v225
	v_and_b32_e32 v225, 8, v165
	v_lshlrev_b32_e32 v225, 2, v225
	v_xor_b32_e32 v224, v224, v225
	v_and_b32_e32 v225, 0xc0, v165
	v_lshl_or_b32 v224, v225, 4, v224
	v_and_b32_e32 v225, 0x100, v165
	v_lshl_or_b32 v224, v225, 11, v224
	v_add_u32_e32 v224, s14, v224
	v_add_u32_e32 v226, 0x1000, v224
	v_fmamk_f32 v166, v248, 0x3a800000, v148
	v_rsq_f32_e32 v166, v166
	s_nop 0
	v_pk_mul_f32 v[124:125], v[124:125], v[166:167] op_sel_hi:[1,0]
	v_pk_mul_f32 v[126:127], v[126:127], v[166:167] op_sel_hi:[1,0]
	v_pk_mul_f32 v[120:121], v[120:121], v[166:167] op_sel_hi:[1,0]
	v_pk_mul_f32 v[122:123], v[122:123], v[166:167] op_sel_hi:[1,0]
	v_pk_mul_f32 v[116:117], v[116:117], v[166:167] op_sel_hi:[1,0]
	v_pk_mul_f32 v[118:119], v[118:119], v[166:167] op_sel_hi:[1,0]
	v_pk_mul_f32 v[112:113], v[112:113], v[166:167] op_sel_hi:[1,0]
	v_pk_mul_f32 v[114:115], v[114:115], v[166:167] op_sel_hi:[1,0]
	v_max_f32_e32 v124, 0, v124
	v_max_f32_e32 v125, 0, v125
	v_max_f32_e32 v126, 0, v126
	v_max_f32_e32 v127, 0, v127
	v_max_f32_e32 v120, 0, v120
	v_max_f32_e32 v121, 0, v121
	v_max_f32_e32 v122, 0, v122
	v_max_f32_e32 v123, 0, v123
	v_max_f32_e32 v116, 0, v116
	v_max_f32_e32 v117, 0, v117
	v_max_f32_e32 v118, 0, v118
	v_max_f32_e32 v119, 0, v119
	v_max_f32_e32 v112, 0, v112
	v_max_f32_e32 v113, 0, v113
	v_max_f32_e32 v114, 0, v114
	v_max_f32_e32 v115, 0, v115
	v_pk_mul_f32 v[124:125], v[124:125], v[124:125]
	v_pk_mul_f32 v[126:127], v[126:127], v[126:127]
	v_pk_mul_f32 v[120:121], v[120:121], v[120:121]
	v_pk_mul_f32 v[122:123], v[122:123], v[122:123]
	v_pk_mul_f32 v[116:117], v[116:117], v[116:117]
	v_pk_mul_f32 v[118:119], v[118:119], v[118:119]
	v_pk_mul_f32 v[112:113], v[112:113], v[112:113]
	v_pk_mul_f32 v[114:115], v[114:115], v[114:115]
	v_cvt_pk_bf16_f32 v124, v124, v125
	v_cvt_pk_bf16_f32 v125, v126, v127
	v_cvt_pk_bf16_f32 v126, v120, v121
	v_cvt_pk_bf16_f32 v127, v122, v123
	v_cvt_pk_bf16_f32 v116, v116, v117
	v_cvt_pk_bf16_f32 v117, v118, v119
	v_cvt_pk_bf16_f32 v118, v112, v113
	v_cvt_pk_bf16_f32 v119, v114, v115
	global_store_dwordx4 v224, v[124:127], s[48:49]
	global_store_dwordx4 v226, v[116:119], s[48:49]
	v_fmamk_f32 v168, v249, 0x3a800000, v148
	v_rsq_f32_e32 v168, v168
	s_nop 0
	v_pk_mul_f32 v[108:109], v[108:109], v[168:169] op_sel_hi:[1,0]
	v_pk_mul_f32 v[110:111], v[110:111], v[168:169] op_sel_hi:[1,0]
	v_pk_mul_f32 v[104:105], v[104:105], v[168:169] op_sel_hi:[1,0]
	v_pk_mul_f32 v[106:107], v[106:107], v[168:169] op_sel_hi:[1,0]
	v_pk_mul_f32 v[100:101], v[100:101], v[168:169] op_sel_hi:[1,0]
	v_pk_mul_f32 v[102:103], v[102:103], v[168:169] op_sel_hi:[1,0]
	v_pk_mul_f32 v[96:97], v[96:97], v[168:169] op_sel_hi:[1,0]
	v_pk_mul_f32 v[98:99], v[98:99], v[168:169] op_sel_hi:[1,0]
	v_max_f32_e32 v108, 0, v108
	v_max_f32_e32 v109, 0, v109
	v_max_f32_e32 v110, 0, v110
	v_max_f32_e32 v111, 0, v111
	v_max_f32_e32 v104, 0, v104
	v_max_f32_e32 v105, 0, v105
	v_max_f32_e32 v106, 0, v106
	v_max_f32_e32 v107, 0, v107
	v_max_f32_e32 v100, 0, v100
	v_max_f32_e32 v101, 0, v101
	v_max_f32_e32 v102, 0, v102
	v_max_f32_e32 v103, 0, v103
	v_max_f32_e32 v96, 0, v96
	v_max_f32_e32 v97, 0, v97
	v_max_f32_e32 v98, 0, v98
	v_max_f32_e32 v99, 0, v99
	v_pk_mul_f32 v[108:109], v[108:109], v[108:109]
	v_pk_mul_f32 v[110:111], v[110:111], v[110:111]
	v_pk_mul_f32 v[104:105], v[104:105], v[104:105]
	v_pk_mul_f32 v[106:107], v[106:107], v[106:107]
	v_pk_mul_f32 v[100:101], v[100:101], v[100:101]
	v_pk_mul_f32 v[102:103], v[102:103], v[102:103]
	v_pk_mul_f32 v[96:97], v[96:97], v[96:97]
	v_pk_mul_f32 v[98:99], v[98:99], v[98:99]
	v_cvt_pk_bf16_f32 v108, v108, v109
	v_cvt_pk_bf16_f32 v109, v110, v111
	v_cvt_pk_bf16_f32 v110, v104, v105
	v_cvt_pk_bf16_f32 v111, v106, v107
	v_cvt_pk_bf16_f32 v100, v100, v101
	v_cvt_pk_bf16_f32 v101, v102, v103
	v_cvt_pk_bf16_f32 v102, v96, v97
	v_cvt_pk_bf16_f32 v103, v98, v99
	v_add_u32_e32 v225, 0x20000, v224
	v_add_u32_e32 v227, 0x20000, v226
	global_store_dwordx4 v225, v[108:111], s[48:49]
	global_store_dwordx4 v227, v[100:103], s[48:49]
	v_fmamk_f32 v170, v250, 0x3a800000, v148
	v_rsq_f32_e32 v170, v170
	s_nop 0
	v_pk_mul_f32 v[92:93], v[92:93], v[170:171] op_sel_hi:[1,0]
	v_pk_mul_f32 v[94:95], v[94:95], v[170:171] op_sel_hi:[1,0]
	v_pk_mul_f32 v[88:89], v[88:89], v[170:171] op_sel_hi:[1,0]
	v_pk_mul_f32 v[90:91], v[90:91], v[170:171] op_sel_hi:[1,0]
	v_pk_mul_f32 v[84:85], v[84:85], v[170:171] op_sel_hi:[1,0]
	v_pk_mul_f32 v[86:87], v[86:87], v[170:171] op_sel_hi:[1,0]
	v_pk_mul_f32 v[80:81], v[80:81], v[170:171] op_sel_hi:[1,0]
	v_pk_mul_f32 v[82:83], v[82:83], v[170:171] op_sel_hi:[1,0]
	v_max_f32_e32 v92, 0, v92
	v_max_f32_e32 v93, 0, v93
	v_max_f32_e32 v94, 0, v94
	v_max_f32_e32 v95, 0, v95
	v_max_f32_e32 v88, 0, v88
	v_max_f32_e32 v89, 0, v89
	v_max_f32_e32 v90, 0, v90
	v_max_f32_e32 v91, 0, v91
	v_max_f32_e32 v84, 0, v84
	v_max_f32_e32 v85, 0, v85
	v_max_f32_e32 v86, 0, v86
	v_max_f32_e32 v87, 0, v87
	v_max_f32_e32 v80, 0, v80
	v_max_f32_e32 v81, 0, v81
	v_max_f32_e32 v82, 0, v82
	v_max_f32_e32 v83, 0, v83
	v_pk_mul_f32 v[92:93], v[92:93], v[92:93]
	v_pk_mul_f32 v[94:95], v[94:95], v[94:95]
	v_pk_mul_f32 v[88:89], v[88:89], v[88:89]
	v_pk_mul_f32 v[90:91], v[90:91], v[90:91]
	v_pk_mul_f32 v[84:85], v[84:85], v[84:85]
	v_pk_mul_f32 v[86:87], v[86:87], v[86:87]
	v_pk_mul_f32 v[80:81], v[80:81], v[80:81]
	v_pk_mul_f32 v[82:83], v[82:83], v[82:83]
	v_cvt_pk_bf16_f32 v92, v92, v93
	v_cvt_pk_bf16_f32 v93, v94, v95
	v_cvt_pk_bf16_f32 v94, v88, v89
	v_cvt_pk_bf16_f32 v95, v90, v91
	v_cvt_pk_bf16_f32 v84, v84, v85
	v_cvt_pk_bf16_f32 v85, v86, v87
	v_cvt_pk_bf16_f32 v86, v80, v81
	v_cvt_pk_bf16_f32 v87, v82, v83
	v_add_u32_e32 v225, 0x40000, v224
	v_add_u32_e32 v227, 0x40000, v226
	global_store_dwordx4 v225, v[92:95], s[48:49]
	global_store_dwordx4 v227, v[84:87], s[48:49]
	v_fmamk_f32 v172, v251, 0x3a800000, v148
	v_rsq_f32_e32 v172, v172
	s_nop 0
	v_pk_mul_f32 v[76:77], v[76:77], v[172:173] op_sel_hi:[1,0]
	v_pk_mul_f32 v[78:79], v[78:79], v[172:173] op_sel_hi:[1,0]
	v_pk_mul_f32 v[72:73], v[72:73], v[172:173] op_sel_hi:[1,0]
	v_pk_mul_f32 v[74:75], v[74:75], v[172:173] op_sel_hi:[1,0]
	v_pk_mul_f32 v[68:69], v[68:69], v[172:173] op_sel_hi:[1,0]
	v_pk_mul_f32 v[70:71], v[70:71], v[172:173] op_sel_hi:[1,0]
	v_pk_mul_f32 v[64:65], v[64:65], v[172:173] op_sel_hi:[1,0]
	v_pk_mul_f32 v[66:67], v[66:67], v[172:173] op_sel_hi:[1,0]
	v_max_f32_e32 v76, 0, v76
	v_max_f32_e32 v77, 0, v77
	v_max_f32_e32 v78, 0, v78
	v_max_f32_e32 v79, 0, v79
	v_max_f32_e32 v72, 0, v72
	v_max_f32_e32 v73, 0, v73
	v_max_f32_e32 v74, 0, v74
	v_max_f32_e32 v75, 0, v75
	v_max_f32_e32 v68, 0, v68
	v_max_f32_e32 v69, 0, v69
	v_max_f32_e32 v70, 0, v70
	v_max_f32_e32 v71, 0, v71
	v_max_f32_e32 v64, 0, v64
	v_max_f32_e32 v65, 0, v65
	v_max_f32_e32 v66, 0, v66
	v_max_f32_e32 v67, 0, v67
	v_pk_mul_f32 v[76:77], v[76:77], v[76:77]
	v_pk_mul_f32 v[78:79], v[78:79], v[78:79]
	v_pk_mul_f32 v[72:73], v[72:73], v[72:73]
	v_pk_mul_f32 v[74:75], v[74:75], v[74:75]
	v_pk_mul_f32 v[68:69], v[68:69], v[68:69]
	v_pk_mul_f32 v[70:71], v[70:71], v[70:71]
	v_pk_mul_f32 v[64:65], v[64:65], v[64:65]
	v_pk_mul_f32 v[66:67], v[66:67], v[66:67]
	v_cvt_pk_bf16_f32 v76, v76, v77
	v_cvt_pk_bf16_f32 v77, v78, v79
	v_cvt_pk_bf16_f32 v78, v72, v73
	v_cvt_pk_bf16_f32 v79, v74, v75
	v_cvt_pk_bf16_f32 v68, v68, v69
	v_cvt_pk_bf16_f32 v69, v70, v71
	v_cvt_pk_bf16_f32 v70, v64, v65
	v_cvt_pk_bf16_f32 v71, v66, v67
	v_add_u32_e32 v225, 0x60000, v224
	v_add_u32_e32 v227, 0x60000, v226
	global_store_dwordx4 v225, v[76:79], s[48:49]
	global_store_dwordx4 v227, v[68:71], s[48:49]
	v_fmamk_f32 v174, v252, 0x3a800000, v148
	v_rsq_f32_e32 v174, v174
	s_nop 0
	v_pk_mul_f32 v[60:61], v[60:61], v[174:175] op_sel_hi:[1,0]
	v_pk_mul_f32 v[62:63], v[62:63], v[174:175] op_sel_hi:[1,0]
	v_pk_mul_f32 v[56:57], v[56:57], v[174:175] op_sel_hi:[1,0]
	v_pk_mul_f32 v[58:59], v[58:59], v[174:175] op_sel_hi:[1,0]
	v_pk_mul_f32 v[52:53], v[52:53], v[174:175] op_sel_hi:[1,0]
	v_pk_mul_f32 v[54:55], v[54:55], v[174:175] op_sel_hi:[1,0]
	v_pk_mul_f32 v[48:49], v[48:49], v[174:175] op_sel_hi:[1,0]
	v_pk_mul_f32 v[50:51], v[50:51], v[174:175] op_sel_hi:[1,0]
	v_max_f32_e32 v60, 0, v60
	v_max_f32_e32 v61, 0, v61
	v_max_f32_e32 v62, 0, v62
	v_max_f32_e32 v63, 0, v63
	v_max_f32_e32 v56, 0, v56
	v_max_f32_e32 v57, 0, v57
	v_max_f32_e32 v58, 0, v58
	v_max_f32_e32 v59, 0, v59
	v_max_f32_e32 v52, 0, v52
	v_max_f32_e32 v53, 0, v53
	v_max_f32_e32 v54, 0, v54
	v_max_f32_e32 v55, 0, v55
	v_max_f32_e32 v48, 0, v48
	v_max_f32_e32 v49, 0, v49
	v_max_f32_e32 v50, 0, v50
	v_max_f32_e32 v51, 0, v51
	v_pk_mul_f32 v[60:61], v[60:61], v[60:61]
	v_pk_mul_f32 v[62:63], v[62:63], v[62:63]
	v_pk_mul_f32 v[56:57], v[56:57], v[56:57]
	v_pk_mul_f32 v[58:59], v[58:59], v[58:59]
	v_pk_mul_f32 v[52:53], v[52:53], v[52:53]
	v_pk_mul_f32 v[54:55], v[54:55], v[54:55]
	v_pk_mul_f32 v[48:49], v[48:49], v[48:49]
	v_pk_mul_f32 v[50:51], v[50:51], v[50:51]
	v_cvt_pk_bf16_f32 v60, v60, v61
	v_cvt_pk_bf16_f32 v61, v62, v63
	v_cvt_pk_bf16_f32 v62, v56, v57
	v_cvt_pk_bf16_f32 v63, v58, v59
	v_cvt_pk_bf16_f32 v52, v52, v53
	v_cvt_pk_bf16_f32 v53, v54, v55
	v_cvt_pk_bf16_f32 v54, v48, v49
	v_cvt_pk_bf16_f32 v55, v50, v51
	v_add_u32_e32 v225, 0x100000, v224
	v_add_u32_e32 v227, 0x100000, v226
	global_store_dwordx4 v225, v[60:63], s[48:49]
	global_store_dwordx4 v227, v[52:55], s[48:49]
	v_fmamk_f32 v176, v253, 0x3a800000, v148
	v_rsq_f32_e32 v176, v176
	s_nop 0
	v_pk_mul_f32 v[44:45], v[44:45], v[176:177] op_sel_hi:[1,0]
	v_pk_mul_f32 v[46:47], v[46:47], v[176:177] op_sel_hi:[1,0]
	v_pk_mul_f32 v[40:41], v[40:41], v[176:177] op_sel_hi:[1,0]
	v_pk_mul_f32 v[42:43], v[42:43], v[176:177] op_sel_hi:[1,0]
	v_pk_mul_f32 v[36:37], v[36:37], v[176:177] op_sel_hi:[1,0]
	v_pk_mul_f32 v[38:39], v[38:39], v[176:177] op_sel_hi:[1,0]
	v_pk_mul_f32 v[32:33], v[32:33], v[176:177] op_sel_hi:[1,0]
	v_pk_mul_f32 v[34:35], v[34:35], v[176:177] op_sel_hi:[1,0]
	v_max_f32_e32 v44, 0, v44
	v_max_f32_e32 v45, 0, v45
	v_max_f32_e32 v46, 0, v46
	v_max_f32_e32 v47, 0, v47
	v_max_f32_e32 v40, 0, v40
	v_max_f32_e32 v41, 0, v41
	v_max_f32_e32 v42, 0, v42
	v_max_f32_e32 v43, 0, v43
	v_max_f32_e32 v36, 0, v36
	v_max_f32_e32 v37, 0, v37
	v_max_f32_e32 v38, 0, v38
	v_max_f32_e32 v39, 0, v39
	v_max_f32_e32 v32, 0, v32
	v_max_f32_e32 v33, 0, v33
	v_max_f32_e32 v34, 0, v34
	v_max_f32_e32 v35, 0, v35
	v_pk_mul_f32 v[44:45], v[44:45], v[44:45]
	v_pk_mul_f32 v[46:47], v[46:47], v[46:47]
	v_pk_mul_f32 v[40:41], v[40:41], v[40:41]
	v_pk_mul_f32 v[42:43], v[42:43], v[42:43]
	v_pk_mul_f32 v[36:37], v[36:37], v[36:37]
	v_pk_mul_f32 v[38:39], v[38:39], v[38:39]
	v_pk_mul_f32 v[32:33], v[32:33], v[32:33]
	v_pk_mul_f32 v[34:35], v[34:35], v[34:35]
	v_cvt_pk_bf16_f32 v44, v44, v45
	v_cvt_pk_bf16_f32 v45, v46, v47
	v_cvt_pk_bf16_f32 v46, v40, v41
	v_cvt_pk_bf16_f32 v47, v42, v43
	v_cvt_pk_bf16_f32 v36, v36, v37
	v_cvt_pk_bf16_f32 v37, v38, v39
	v_cvt_pk_bf16_f32 v38, v32, v33
	v_cvt_pk_bf16_f32 v39, v34, v35
	v_add_u32_e32 v225, 0x120000, v224
	v_add_u32_e32 v227, 0x120000, v226
	global_store_dwordx4 v225, v[44:47], s[48:49]
	global_store_dwordx4 v227, v[36:39], s[48:49]
	v_fmamk_f32 v178, v254, 0x3a800000, v148
	v_rsq_f32_e32 v178, v178
	s_nop 0
	v_pk_mul_f32 v[28:29], v[28:29], v[178:179] op_sel_hi:[1,0]
	v_pk_mul_f32 v[30:31], v[30:31], v[178:179] op_sel_hi:[1,0]
	v_pk_mul_f32 v[24:25], v[24:25], v[178:179] op_sel_hi:[1,0]
	v_pk_mul_f32 v[26:27], v[26:27], v[178:179] op_sel_hi:[1,0]
	v_pk_mul_f32 v[20:21], v[20:21], v[178:179] op_sel_hi:[1,0]
	v_pk_mul_f32 v[22:23], v[22:23], v[178:179] op_sel_hi:[1,0]
	v_pk_mul_f32 v[16:17], v[16:17], v[178:179] op_sel_hi:[1,0]
	v_pk_mul_f32 v[18:19], v[18:19], v[178:179] op_sel_hi:[1,0]
	v_max_f32_e32 v28, 0, v28
	v_max_f32_e32 v29, 0, v29
	v_max_f32_e32 v30, 0, v30
	v_max_f32_e32 v31, 0, v31
	v_max_f32_e32 v24, 0, v24
	v_max_f32_e32 v25, 0, v25
	v_max_f32_e32 v26, 0, v26
	v_max_f32_e32 v27, 0, v27
	v_max_f32_e32 v20, 0, v20
	v_max_f32_e32 v21, 0, v21
	v_max_f32_e32 v22, 0, v22
	v_max_f32_e32 v23, 0, v23
	v_max_f32_e32 v16, 0, v16
	v_max_f32_e32 v17, 0, v17
	v_max_f32_e32 v18, 0, v18
	v_max_f32_e32 v19, 0, v19
	v_pk_mul_f32 v[28:29], v[28:29], v[28:29]
	v_pk_mul_f32 v[30:31], v[30:31], v[30:31]
	v_pk_mul_f32 v[24:25], v[24:25], v[24:25]
	v_pk_mul_f32 v[26:27], v[26:27], v[26:27]
	v_pk_mul_f32 v[20:21], v[20:21], v[20:21]
	v_pk_mul_f32 v[22:23], v[22:23], v[22:23]
	v_pk_mul_f32 v[16:17], v[16:17], v[16:17]
	v_pk_mul_f32 v[18:19], v[18:19], v[18:19]
	v_cvt_pk_bf16_f32 v28, v28, v29
	v_cvt_pk_bf16_f32 v29, v30, v31
	v_cvt_pk_bf16_f32 v30, v24, v25
	v_cvt_pk_bf16_f32 v31, v26, v27
	v_cvt_pk_bf16_f32 v20, v20, v21
	v_cvt_pk_bf16_f32 v21, v22, v23
	v_cvt_pk_bf16_f32 v22, v16, v17
	v_cvt_pk_bf16_f32 v23, v18, v19
	v_add_u32_e32 v225, 0x140000, v224
	v_add_u32_e32 v227, 0x140000, v226
	global_store_dwordx4 v225, v[28:31], s[48:49]
	global_store_dwordx4 v227, v[20:23], s[48:49]
	v_fmamk_f32 v180, v255, 0x3a800000, v148
	v_rsq_f32_e32 v180, v180
	s_nop 0
	v_pk_mul_f32 v[12:13], v[12:13], v[180:181] op_sel_hi:[1,0]
	v_pk_mul_f32 v[14:15], v[14:15], v[180:181] op_sel_hi:[1,0]
	v_pk_mul_f32 v[8:9], v[8:9], v[180:181] op_sel_hi:[1,0]
	v_pk_mul_f32 v[10:11], v[10:11], v[180:181] op_sel_hi:[1,0]
	v_pk_mul_f32 v[4:5], v[4:5], v[180:181] op_sel_hi:[1,0]
	v_pk_mul_f32 v[6:7], v[6:7], v[180:181] op_sel_hi:[1,0]
	v_pk_mul_f32 v[0:1], v[0:1], v[180:181] op_sel_hi:[1,0]
	v_pk_mul_f32 v[2:3], v[2:3], v[180:181] op_sel_hi:[1,0]
	v_max_f32_e32 v12, 0, v12
	v_max_f32_e32 v13, 0, v13
	v_max_f32_e32 v14, 0, v14
	v_max_f32_e32 v15, 0, v15
	v_max_f32_e32 v8, 0, v8
	v_max_f32_e32 v9, 0, v9
	v_max_f32_e32 v10, 0, v10
	v_max_f32_e32 v11, 0, v11
	v_max_f32_e32 v4, 0, v4
	v_max_f32_e32 v5, 0, v5
	v_max_f32_e32 v6, 0, v6
	v_max_f32_e32 v7, 0, v7
	v_max_f32_e32 v0, 0, v0
	v_max_f32_e32 v1, 0, v1
	v_max_f32_e32 v2, 0, v2
	v_max_f32_e32 v3, 0, v3
	v_pk_mul_f32 v[12:13], v[12:13], v[12:13]
	v_pk_mul_f32 v[14:15], v[14:15], v[14:15]
	v_pk_mul_f32 v[8:9], v[8:9], v[8:9]
	v_pk_mul_f32 v[10:11], v[10:11], v[10:11]
	v_pk_mul_f32 v[4:5], v[4:5], v[4:5]
	v_pk_mul_f32 v[6:7], v[6:7], v[6:7]
	v_pk_mul_f32 v[0:1], v[0:1], v[0:1]
	v_pk_mul_f32 v[2:3], v[2:3], v[2:3]
	v_cvt_pk_bf16_f32 v12, v12, v13
	v_cvt_pk_bf16_f32 v13, v14, v15
	v_cvt_pk_bf16_f32 v14, v8, v9
	v_cvt_pk_bf16_f32 v15, v10, v11
	v_cvt_pk_bf16_f32 v4, v4, v5
	v_cvt_pk_bf16_f32 v5, v6, v7
	v_cvt_pk_bf16_f32 v6, v0, v1
	v_cvt_pk_bf16_f32 v7, v2, v3
	v_add_u32_e32 v225, 0x160000, v224
	v_add_u32_e32 v227, 0x160000, v226
	global_store_dwordx4 v225, v[12:15], s[48:49]
	global_store_dwordx4 v227, v[4:7], s[48:49]
	s_mov_b32 s11, 0x160000
	s_andn2_b64 vcc, exec, s[36:37]
	s_mov_b64 s[14:15], -1
	s_cbranch_vccnz .LBB0_656
	s_andn2_b64 vcc, exec, s[4:5]
	s_cbranch_vccnz .LBB0_655
	s_barrier
	s_branch .LBB0_655

	.amdhsa_kernel _Z4mega6Params
		.amdhsa_group_segment_fixed_size 0
		.amdhsa_private_segment_fixed_size 0
		.amdhsa_kernarg_size 488
		.amdhsa_user_sgpr_count 2
		.amdhsa_user_sgpr_dispatch_ptr 0
		.amdhsa_user_sgpr_queue_ptr 0
		.amdhsa_user_sgpr_kernarg_segment_ptr 1
		.amdhsa_user_sgpr_dispatch_id 0
		.amdhsa_user_sgpr_kernarg_preload_length 0
		.amdhsa_user_sgpr_kernarg_preload_offset 0
		.amdhsa_user_sgpr_private_segment_size 0
		.amdhsa_uses_dynamic_stack 0
		.amdhsa_enable_private_segment 0
		.amdhsa_system_sgpr_workgroup_id_x 1
		.amdhsa_system_sgpr_workgroup_id_y 0
		.amdhsa_system_sgpr_workgroup_id_z 0
		.amdhsa_system_sgpr_workgroup_info 0
		.amdhsa_system_vgpr_workitem_id 2
		.amdhsa_next_free_vgpr 256
		.amdhsa_next_free_sgpr 98
		.amdhsa_accum_offset 256
		.amdhsa_reserve_vcc 1
		.amdhsa_float_round_mode_32 0
		.amdhsa_float_round_mode_16_64 0
		.amdhsa_float_denorm_mode_32 3
		.amdhsa_float_denorm_mode_16_64 3
		.amdhsa_dx10_clamp 1
		.amdhsa_ieee_mode 1
		.amdhsa_fp16_overflow 0
		.amdhsa_tg_split 0
		.amdhsa_exception_fp_ieee_invalid_op 0
		.amdhsa_exception_fp_denorm_src 0
		.amdhsa_exception_fp_ieee_div_zero 0
		.amdhsa_exception_fp_ieee_overflow 0
		.amdhsa_exception_fp_ieee_underflow 0
		.amdhsa_exception_fp_ieee_inexact 0
		.amdhsa_exception_int_div_zero 0
	.end_amdhsa_kernel

amdhsa.kernels:
  - .agpr_count:     0
    .args:
      - .offset:         0
        .size:           232
        .value_kind:     by_value
      - .offset:         232
        .size:           4
        .value_kind:     hidden_block_count_x
      - .offset:         236
        .size:           4
        .value_kind:     hidden_block_count_y
      - .offset:         240
        .size:           4
        .value_kind:     hidden_block_count_z
      - .offset:         244
        .size:           2
        .value_kind:     hidden_group_size_x
      - .offset:         246
        .size:           2
        .value_kind:     hidden_group_size_y
      - .offset:         248
        .size:           2
        .value_kind:     hidden_group_size_z
      - .offset:         250
        .size:           2
        .value_kind:     hidden_remainder_x
      - .offset:         252
        .size:           2
        .value_kind:     hidden_remainder_y
      - .offset:         254
        .size:           2
        .value_kind:     hidden_remainder_z
      - .offset:         272
        .size:           8
        .value_kind:     hidden_global_offset_x
      - .offset:         280
        .size:           8
        .value_kind:     hidden_global_offset_y
      - .offset:         288
        .size:           8
        .value_kind:     hidden_global_offset_z
      - .offset:         296
        .size:           2
        .value_kind:     hidden_grid_dims
      - .offset:         320
        .size:           8
        .value_kind:     hidden_multigrid_sync_arg
      - .offset:         352
        .size:           4
        .value_kind:     hidden_dynamic_lds_size
    .group_segment_fixed_size: 0
    .kernarg_segment_align: 8
    .kernarg_segment_size: 488
    .language:       OpenCL C
    .language_version:
      - 2
      - 0
    .max_flat_workgroup_size: 512
    .name:           _Z4mega6Params
    .private_segment_fixed_size: 0
    .sgpr_count:     104
    .sgpr_spill_count: 69
    .symbol:         _Z4mega6Params.kd
    .uniform_work_group_size: 1
    .uses_dynamic_stack: false
    .vgpr_count:     256
    .vgpr_spill_count: 0
    .wavefront_size: 64
